# gdn scan producer: progressive counted waits, each tile written to LDS as soon as its own load has landed
# speedup vs baseline: 1.0061x; 1.0061x over previous
; #define LDS_BARRIER() do { asm volatile("s_waitcnt lgkmcnt(0)" ::: "memory"); __builtin_amdgcn_s_barrier(); asm volatile("" ::: "memory"); } while (0)
; #define GDN_STORE_O(nn) do { const LAS bf16_t* ob_ = OTb + ((nn) & 1) * 4608; _Pragma("unroll") for (int k_ = 0; k_ < 2; ++k_) { const int vi_ = pt_ + 256 * k_, row_ = vi_ >> 3, c8_ = (vi_ & 7) * 8; \
;             *(u32x4*)(Y + (size_t)(b * T_ + 64 * (nn) + row_) * D_ + 256 + h * 128 + 64 * dvh + c8_) = *(const LAS u32x4*)(ob_ + row_ * 72 + c8_); } } while (0)
; __device__ __forceinline__ void gdn_scan(const Ctx& c, const Params& p, int e) {
;     ...
;         if (producer) {
;             int pt_ = ptid; asm volatile("" : "+v"(pt_));
;             u32x4 tq[4], tk[4], tw[4], tu[4], tqk[2];
;             const int prow = pt_ >> 4, pc8 = (pt_ & 15) * 8;
;             const int qrow = pt_ >> 3, qc8 = (pt_ & 7) * 8;
;             GDN_LOAD_TILES(0); GDN_STORE_TILES();
;             for (int n = 0; n < 128; ++n) {
;                 LDS_BARRIER();
;                 if (n + 1 < 128) GDN_LOAD_TILES(n + 1);
;                 if (n >= 1) GDN_STORE_O(n - 1);
;                 LDS_BARRIER();
;                 if (n + 1 < 128) GDN_STORE_TILES();
;             }
.Lgp_e_nold:
	s_add_i32 s2, s2, 1
	s_waitcnt lgkmcnt(0)
	s_barrier
	v_add_u32_e32 v72, 64, v72
	v_add_u32_e32 v74, 64, v74
	s_cmpk_eq_i32 s2, 0x7e
	s_cbranch_scc0 .Lgp_e_wr
	s_waitcnt vmcnt(0)
.Lgp_e_wr:
	s_waitcnt vmcnt(35)
	ds_write_b128 v91, v[116:119]
	s_waitcnt vmcnt(34)
	ds_write_b128 v91, v[120:123] offset:17408
	s_waitcnt vmcnt(33)
	ds_write_b128 v91, v[124:127] offset:34816
	s_waitcnt vmcnt(32)
	ds_write_b128 v92, v[128:131] offset:52224
	s_waitcnt vmcnt(31)
	ds_write_b128 v91, v[132:135] offset:4352
	s_waitcnt vmcnt(30)
	ds_write_b128 v91, v[136:139] offset:21760
	s_waitcnt vmcnt(29)
	ds_write_b128 v91, v[140:143] offset:39168
	s_waitcnt vmcnt(28)
	ds_write_b128 v93, v[200:203] offset:52224
	s_waitcnt vmcnt(27)
	ds_write_b128 v91, v[204:207] offset:8704
	s_waitcnt vmcnt(26)
	ds_write_b128 v91, v[208:211] offset:26112
	s_waitcnt vmcnt(25)
	ds_write_b128 v91, v[212:215] offset:43520
	s_waitcnt vmcnt(24)
	ds_write_b128 v94, v[216:219] offset:52224
	s_waitcnt vmcnt(23)
	ds_write_b128 v91, v[220:223] offset:13056
	s_waitcnt vmcnt(22)
	ds_write_b128 v91, v[224:227] offset:30464
	s_waitcnt vmcnt(21)
	ds_write_b128 v91, v[228:231] offset:47872
	s_waitcnt vmcnt(20)
	ds_write_b128 v95, v[232:235] offset:52224
	s_waitcnt vmcnt(19)
	ds_write_b128 v96, v[236:239]
	s_waitcnt vmcnt(18)
	ds_write_b128 v96, v[240:243] offset:4608
	s_cmpk_eq_i32 s2, 0x7e
	s_cbranch_scc1 .Lgp_done
	s_waitcnt lgkmcnt(0)
	s_barrier
	s_bitcmp1_b32 s2, 0
	s_cselect_b32 s3, 0x2400, 0
	v_add_u32_e32 v73, s3, v69
	v_add_u32_e32 v75, v73, v90
	ds_read_b128 v[106:109], v75
	v_ashrrev_i32_e32 v75, 31, v74
	v_lshlrev_b64 v[110:111], 11, v[74:75]
	v_lshl_add_u64 v[110:111], v[70:71], 0, v[110:111]
	v_add_u32_e32 v73, v73, v67
	s_waitcnt lgkmcnt(0)
	global_store_dwordx4 v[110:111], v[106:109], off offset:512
	ds_read_b128 v[106:109], v73
	v_ashrrev_i32_e32 v73, 31, v72
	v_lshlrev_b64 v[110:111], 11, v[72:73]
	v_lshl_add_u64 v[110:111], v[70:71], 0, v[110:111]
	s_waitcnt lgkmcnt(0)
	global_store_dwordx4 v[110:111], v[106:109], off offset:512
	global_load_dwordx4 v[116:119], v244, s[20:21] offset:1536
	global_load_dwordx4 v[120:123], v245, s[40:41]
	s_mov_b64 exec, s[98:99]
	global_load_dwordx4 v[124:127], v246, s[40:41]
	s_mov_b64 exec, -1
	global_load_dwordx4 v[128:131], v247, s[20:21]
	global_load_dwordx4 v[132:135], v248, s[20:21] offset:2048
	global_load_dwordx4 v[136:139], v249, s[40:41]
	s_mov_b64 exec, s[98:99]
	global_load_dwordx4 v[140:143], v250, s[40:41]
	s_mov_b64 exec, -1
	global_load_dwordx4 v[200:203], v251, s[20:21]
	global_load_dwordx4 v[204:207], v252, s[20:21] offset:2560
	global_load_dwordx4 v[208:211], v253, s[40:41]
	s_mov_b64 exec, s[98:99]
	global_load_dwordx4 v[212:215], v112, s[40:41]
	s_mov_b64 exec, -1
	global_load_dwordx4 v[216:219], v113, s[20:21]
	global_load_dwordx4 v[220:223], v114, s[20:21] offset:3072
	global_load_dwordx4 v[224:227], v115, s[40:41]
	s_mov_b64 exec, s[98:99]
	global_load_dwordx4 v[228:231], v76, s[40:41]
	s_mov_b64 exec, -1
	global_load_dwordx4 v[232:235], v77, s[20:21]
	global_load_dwordx4 v[236:239], v78, s[20:21] offset:512
	global_load_dwordx4 v[240:243], v79, s[20:21] offset:1536
	s_add_u32 s20, s20, 0x78800
	s_addc_u32 s21, s21, 0
	s_add_u32 s40, s40, 0x18000
	s_addc_u32 s41, s41, 0
	s_add_i32 s2, s2, 1
	s_waitcnt lgkmcnt(0)
	s_barrier
	v_add_u32_e32 v72, 64, v72
	v_add_u32_e32 v74, 64, v74
	s_waitcnt vmcnt(35)
	ds_write_b128 v91, v[2:5]
	s_waitcnt vmcnt(34)
	ds_write_b128 v91, v[10:13] offset:17408
	s_waitcnt vmcnt(33)
	ds_write_b128 v91, v[14:17] offset:34816
	s_waitcnt vmcnt(32)
	ds_write_b128 v92, v[6:9] offset:52224
	s_waitcnt vmcnt(31)
	ds_write_b128 v91, v[18:21] offset:4352
	s_waitcnt vmcnt(30)
	ds_write_b128 v91, v[26:29] offset:21760
	s_waitcnt vmcnt(29)
	ds_write_b128 v91, v[30:33] offset:39168
	s_waitcnt vmcnt(28)
	ds_write_b128 v93, v[22:25] offset:52224
	s_waitcnt vmcnt(27)
	ds_write_b128 v91, v[34:37] offset:8704
	s_waitcnt vmcnt(26)
	ds_write_b128 v91, v[42:45] offset:26112
	s_waitcnt vmcnt(25)
	ds_write_b128 v91, v[46:49] offset:43520
	s_waitcnt vmcnt(24)
	ds_write_b128 v94, v[38:41] offset:52224
	s_waitcnt vmcnt(23)
	ds_write_b128 v91, v[50:53] offset:13056
	s_waitcnt vmcnt(22)
	ds_write_b128 v91, v[58:61] offset:30464
	s_waitcnt vmcnt(21)
	ds_write_b128 v91, v[62:65] offset:47872
	s_waitcnt vmcnt(20)
	ds_write_b128 v95, v[54:57] offset:52224
	s_waitcnt vmcnt(19)
	ds_write_b128 v96, v[98:101]
	s_waitcnt vmcnt(18)
	ds_write_b128 v96, v[102:105] offset:4608
	s_branch .Lgp_even
